# v13 + mini-tile K loop: fourth k-step operand loads issued with the first batch
# speedup vs baseline: 1.0187x; 1.0024x over previous
.LBB0_1643:
	v_lshl_add_u64 v[14:15], v[74:75], 0, s[16:17]
	s_waitcnt vmcnt(2)
	v_add_co_u32_e32 v2, vcc, s30, v14
	v_lshl_add_u64 v[80:81], v[76:77], 0, s[16:17]
	s_mov_b64 s[6:7], vcc
	v_add_co_u32_e32 v4, vcc, 0x580000, v80
	v_lshl_add_u64 v[82:83], v[78:79], 0, s[16:17]
	s_mov_b64 s[8:9], vcc
	s_waitcnt vmcnt(0)
	v_add_co_u32_e32 v6, vcc, 0x1840000, v82
	s_add_i32 s37, s35, 0xfffffe80
	s_nop 0
	v_addc_co_u32_e32 v7, vcc, 0, v83, vcc
	global_load_dwordx4 v[90:93], v[6:7], off offset:2048
	v_addc_co_u32_e64 v5, vcc, 0, v81, s[8:9]
	global_load_dwordx4 v[6:9], v[4:5], off
	s_add_i32 s38, s35, 0xffffff80
	s_cmp_lt_i32 s36, 48
	s_cselect_b64 s[8:9], -1, 0
	v_addc_co_u32_e64 v3, vcc, 0, v15, s[6:7]
	s_and_b64 s[6:7], s[8:9], exec
	s_cselect_b32 s6, s38, s37
	s_ashr_i32 s7, s6, 31
	global_load_dwordx4 v[94:97], v[2:3], off
	s_lshl_b64 s[6:7], s[6:7], 1
	s_cmp_lt_i32 s36, 40
	v_lshl_add_u64 v[2:3], v[68:69], 0, s[6:7]
	v_lshl_add_u64 v[4:5], v[70:71], 0, s[6:7]
	v_lshl_add_u64 v[10:11], v[72:73], 0, s[6:7]
	s_cselect_b64 s[6:7], -1, 0
	s_and_b64 s[38:39], s[6:7], exec
	s_cselect_b32 s38, s35, s37
	s_ashr_i32 s39, s38, 31
	s_lshl_b64 s[38:39], s[38:39], 1
	global_load_dwordx4 v[48:51], v[2:3], off
	global_load_dwordx4 v[52:55], v[4:5], off
	v_lshl_add_u64 v[2:3], v[68:69], 0, s[38:39]
	v_lshl_add_u64 v[12:13], v[70:71], 0, s[38:39]
	v_lshl_add_u64 v[98:99], v[72:73], 0, s[38:39]
	global_load_dwordx4 v[56:59], v[10:11], off
	s_nop 0
	global_load_dwordx4 v[2:5], v[2:3], off
	s_cmp_gt_i32 s36, 55
	s_waitcnt vmcnt(5)
	v_mfma_f32_32x32x16_bf16 v[16:31], v[90:93], v[6:9], v[16:31]
	global_load_dwordx4 v[10:13], v[12:13], off
	s_nop 0
	global_load_dwordx4 v[6:9], v[98:99], off
	s_waitcnt vmcnt(6)
	s_cbranch_scc1 .Lmini0_nohoist
	v_add_co_u32_e32 v14, vcc, 0x580000, v14
	s_nop 1
	v_addc_co_u32_e32 v15, vcc, 0, v15, vcc
	v_add_co_u32_e32 v100, vcc, 0x580000, v80
	s_nop 1
	v_addc_co_u32_e32 v101, vcc, 0, v81, vcc
	v_add_co_u32_e32 v80, vcc, 0x1840000, v82
	s_nop 1
	v_addc_co_u32_e32 v81, vcc, 0, v83, vcc
	global_load_dwordx4 v[80:83], v[80:81], off offset:2304
	s_nop 0
	global_load_dwordx4 v[104:107], v[100:101], off offset:256
	global_load_dwordx4 v[108:111], v[14:15], off offset:256
.Lmini0_nohoist:
	v_mfma_f32_32x32x16_bf16 v[32:47], v[90:93], v[94:97], v[32:47]
	s_cbranch_scc1 .LBB0_1649
	s_waitcnt vmcnt(1)
	v_mfma_f32_32x32x16_bf16 v[16:31], v[80:83], v[104:107], v[16:31]
	s_waitcnt vmcnt(0)
	v_mfma_f32_32x32x16_bf16 v[32:47], v[80:83], v[108:111], v[32:47]
	s_andn2_b64 vcc, exec, s[8:9]
	s_cbranch_vccz .LBB0_1650

.LBB0_1767:
	v_lshl_add_u64 v[14:15], v[76:77], 0, s[20:21]
	s_waitcnt vmcnt(2)
	v_add_co_u32_e32 v2, vcc, s34, v14
	v_lshl_add_u64 v[82:83], v[78:79], 0, s[20:21]
	s_mov_b64 s[6:7], vcc
	v_add_co_u32_e32 v4, vcc, 0x780000, v82
	v_lshl_add_u64 v[84:85], v[80:81], 0, s[20:21]
	s_mov_b64 s[8:9], vcc
	s_waitcnt vmcnt(0)
	v_add_co_u32_e32 v6, vcc, 0x199c0000, v84
	s_add_i32 s39, s37, 0xfffffe80
	s_nop 0
	v_addc_co_u32_e32 v7, vcc, 0, v85, vcc
	global_load_dwordx4 v[90:93], v[6:7], off offset:2048
	v_addc_co_u32_e64 v5, vcc, 0, v83, s[8:9]
	global_load_dwordx4 v[6:9], v[4:5], off
	s_add_i32 s40, s37, 0xffffff80
	s_cmp_lt_i32 s38, 48
	s_cselect_b64 s[8:9], -1, 0
	v_addc_co_u32_e64 v3, vcc, 0, v15, s[6:7]
	s_and_b64 s[6:7], s[8:9], exec
	s_cselect_b32 s6, s40, s39
	s_ashr_i32 s7, s6, 31
	global_load_dwordx4 v[94:97], v[2:3], off
	s_lshl_b64 s[6:7], s[6:7], 1
	s_cmp_lt_i32 s38, 40
	v_lshl_add_u64 v[2:3], v[70:71], 0, s[6:7]
	v_lshl_add_u64 v[4:5], v[72:73], 0, s[6:7]
	v_lshl_add_u64 v[10:11], v[74:75], 0, s[6:7]
	s_cselect_b64 s[6:7], -1, 0
	s_and_b64 s[40:41], s[6:7], exec
	s_cselect_b32 s40, s37, s39
	s_ashr_i32 s41, s40, 31
	s_lshl_b64 s[40:41], s[40:41], 1
	global_load_dwordx4 v[48:51], v[2:3], off
	global_load_dwordx4 v[52:55], v[4:5], off
	v_lshl_add_u64 v[2:3], v[70:71], 0, s[40:41]
	v_lshl_add_u64 v[12:13], v[72:73], 0, s[40:41]
	v_lshl_add_u64 v[98:99], v[74:75], 0, s[40:41]
	global_load_dwordx4 v[56:59], v[10:11], off
	s_nop 0
	global_load_dwordx4 v[2:5], v[2:3], off
	s_cmp_gt_i32 s38, 55
	s_waitcnt vmcnt(5)
	v_mfma_f32_32x32x16_bf16 v[16:31], v[90:93], v[6:9], v[16:31]
	global_load_dwordx4 v[10:13], v[12:13], off
	s_nop 0
	global_load_dwordx4 v[6:9], v[98:99], off
	s_waitcnt vmcnt(6)
	s_cbranch_scc1 .Lmini1_nohoist
	v_add_co_u32_e32 v14, vcc, 0x780000, v14
	s_nop 1
	v_addc_co_u32_e32 v15, vcc, 0, v15, vcc
	v_add_co_u32_e32 v100, vcc, 0x780000, v82
	s_nop 1
	v_addc_co_u32_e32 v101, vcc, 0, v83, vcc
	v_add_co_u32_e32 v82, vcc, 0x199c0000, v84
	s_nop 1
	v_addc_co_u32_e32 v83, vcc, 0, v85, vcc
	global_load_dwordx4 v[82:85], v[82:83], off offset:2304
	s_nop 0
	global_load_dwordx4 v[104:107], v[100:101], off offset:256
	global_load_dwordx4 v[108:111], v[14:15], off offset:256
.Lmini1_nohoist:
	v_mfma_f32_32x32x16_bf16 v[32:47], v[90:93], v[94:97], v[32:47]
	s_cbranch_scc1 .LBB0_1773
	s_waitcnt vmcnt(1)
	v_mfma_f32_32x32x16_bf16 v[16:31], v[82:85], v[104:107], v[16:31]
	s_waitcnt vmcnt(0)
	v_mfma_f32_32x32x16_bf16 v[32:47], v[82:85], v[108:111], v[32:47]
	s_andn2_b64 vcc, exec, s[8:9]
	s_cbranch_vccz .LBB0_1774

.LBB0_1806:
	v_lshl_add_u64 v[14:15], v[74:75], 0, s[20:21]
	s_waitcnt vmcnt(2)
	v_add_co_u32_e32 v2, vcc, s35, v14
	v_lshl_add_u64 v[80:81], v[76:77], 0, s[20:21]
	s_mov_b64 s[8:9], vcc
	v_add_co_u32_e32 v4, vcc, 0x1280000, v80
	v_lshl_add_u64 v[82:83], v[78:79], 0, s[20:21]
	s_mov_b64 s[10:11], vcc
	s_waitcnt vmcnt(0)
	v_add_co_u32_e32 v6, vcc, 0x21a40000, v82
	s_add_i32 s39, s37, 0xfffffe80
	s_nop 0
	v_addc_co_u32_e32 v7, vcc, 0, v83, vcc
	global_load_dwordx4 v[90:93], v[6:7], off offset:2048
	v_addc_co_u32_e64 v5, vcc, 0, v81, s[10:11]
	global_load_dwordx4 v[6:9], v[4:5], off
	s_add_i32 s40, s37, 0xffffff80
	s_cmpk_lt_i32 s38, 0xa0
	s_cselect_b64 s[10:11], -1, 0
	v_addc_co_u32_e64 v3, vcc, 0, v15, s[8:9]
	s_and_b64 s[8:9], s[10:11], exec
	s_cselect_b32 s8, s40, s39
	s_ashr_i32 s9, s8, 31
	global_load_dwordx4 v[94:97], v[2:3], off
	s_lshl_b64 s[8:9], s[8:9], 1
	s_cmpk_lt_i32 s38, 0x98
	v_lshl_add_u64 v[2:3], v[68:69], 0, s[8:9]
	v_lshl_add_u64 v[4:5], v[70:71], 0, s[8:9]
	v_lshl_add_u64 v[10:11], v[72:73], 0, s[8:9]
	s_cselect_b64 s[8:9], -1, 0
	s_and_b64 s[40:41], s[8:9], exec
	s_cselect_b32 s40, s37, s39
	s_ashr_i32 s41, s40, 31
	s_lshl_b64 s[40:41], s[40:41], 1
	global_load_dwordx4 v[48:51], v[2:3], off
	global_load_dwordx4 v[52:55], v[4:5], off
	v_lshl_add_u64 v[2:3], v[68:69], 0, s[40:41]
	v_lshl_add_u64 v[12:13], v[70:71], 0, s[40:41]
	v_lshl_add_u64 v[98:99], v[72:73], 0, s[40:41]
	global_load_dwordx4 v[56:59], v[10:11], off
	s_nop 0
	global_load_dwordx4 v[2:5], v[2:3], off
	s_cmpk_gt_i32 s38, 0xa7
	s_waitcnt vmcnt(5)
	v_mfma_f32_32x32x16_bf16 v[16:31], v[90:93], v[6:9], v[16:31]
	global_load_dwordx4 v[10:13], v[12:13], off
	s_nop 0
	global_load_dwordx4 v[6:9], v[98:99], off
	s_waitcnt vmcnt(6)
	s_cbranch_scc1 .Lmini2_nohoist
	v_add_co_u32_e32 v14, vcc, 0x1280000, v14
	s_nop 1
	v_addc_co_u32_e32 v15, vcc, 0, v15, vcc
	v_add_co_u32_e32 v100, vcc, 0x1280000, v80
	s_nop 1
	v_addc_co_u32_e32 v101, vcc, 0, v81, vcc
	v_add_co_u32_e32 v80, vcc, 0x21a40000, v82
	s_nop 1
	v_addc_co_u32_e32 v81, vcc, 0, v83, vcc
	global_load_dwordx4 v[80:83], v[80:81], off offset:2304
	s_nop 0
	global_load_dwordx4 v[104:107], v[100:101], off offset:256
	global_load_dwordx4 v[108:111], v[14:15], off offset:256
.Lmini2_nohoist:
	v_mfma_f32_32x32x16_bf16 v[32:47], v[90:93], v[94:97], v[32:47]
	s_cbranch_scc1 .LBB0_1812
	s_waitcnt vmcnt(1)
	v_mfma_f32_32x32x16_bf16 v[16:31], v[80:83], v[104:107], v[16:31]
	s_waitcnt vmcnt(0)
	v_mfma_f32_32x32x16_bf16 v[32:47], v[80:83], v[108:111], v[32:47]
	s_andn2_b64 vcc, exec, s[10:11]
	s_cbranch_vccz .LBB0_1813
